# P5 and P6 epilogue stores marked sc1 (write-through) so the seam release has less dirty L2 data
# baseline (speedup 1.0000x reference)
.LBB0_592:
	s_add_u32 s4, s92, 0x5200000
	s_addc_u32 s5, s93, 0
	s_lshl_b32 s0, s2, 5
	s_lshl_b32 s1, s8, 8
	s_lshl_b32 s9, s10, 8
	s_or_b32 s0, s1, s0
	v_add_u32_e32 v132, s9, v150
	v_and_or_b32 v130, v151, 24, s0
	v_ashrrev_i32_e32 v133, 31, v132
	v_ashrrev_i32_e32 v131, 31, v130
	v_lshlrev_b64 v[132:133], 11, v[132:133]
	v_lshl_add_u64 v[132:133], v[132:133], 0, v[130:131]
	v_lshlrev_b64 v[136:137], 1, v[132:133]
	v_lshl_add_u64 v[138:139], s[90:91], 0, v[136:137]
	s_barrier
	global_load_dwordx4 v[156:159], v[138:139], off nt
	global_load_dwordx4 v[160:163], v[138:139], off offset:256 nt
	s_add_u32 s12, s90, 0x10000
	s_addc_u32 s13, s91, 0
	global_load_dwordx4 v[164:167], v136, s[12:13] nt
	global_load_dwordx4 v[168:171], v136, s[12:13] offset:256 nt
	s_add_u32 s12, s90, 0x20000
	s_addc_u32 s13, s91, 0
	global_load_dwordx4 v[172:175], v136, s[12:13] nt
	global_load_dwordx4 v[176:179], v136, s[12:13] offset:256 nt
	s_add_u32 s12, s90, 0x30000
	s_addc_u32 s13, s91, 0
	global_load_dwordx4 v[180:183], v136, s[12:13] nt
	global_load_dwordx4 v[184:187], v136, s[12:13] offset:256 nt
	s_add_u32 s12, s90, 0x80000
	s_addc_u32 s13, s91, 0
	global_load_dwordx4 v[188:191], v136, s[12:13] nt
	global_load_dwordx4 v[192:195], v136, s[12:13] offset:256 nt
	s_add_u32 s12, s90, 0x90000
	s_addc_u32 s13, s91, 0
	global_load_dwordx4 v[196:199], v136, s[12:13] nt
	global_load_dwordx4 v[200:203], v136, s[12:13] offset:256 nt
	s_add_u32 s12, s90, 0xa0000
	s_addc_u32 s13, s91, 0
	global_load_dwordx4 v[204:207], v136, s[12:13] nt
	global_load_dwordx4 v[208:211], v136, s[12:13] offset:256 nt
	s_add_u32 s12, s90, 0xb0000
	s_addc_u32 s13, s91, 0
	global_load_dwordx4 v[212:215], v136, s[12:13] nt
	global_load_dwordx4 v[216:219], v136, s[12:13] offset:256 nt
	v_lshl_add_u64 v[136:137], s[4:5], 0, v[136:137]
	s_lshl_b32 s0, s2, 2
	s_add_i32 s2, s0, 0
	v_cmp_gt_u32_e32 vcc, 16, v128
	s_waitcnt vmcnt(15)
	v_mov_b64_e32 v[132:133], v[156:157]
	v_mov_b64_e32 v[134:135], v[158:159]
	v_lshlrev_b32_e32 v140, 16, v132
	v_and_b32_e32 v141, 0xffff0000, v132
	v_lshlrev_b32_e32 v132, 16, v133
	v_and_b32_e32 v133, 0xffff0000, v133
	v_lshlrev_b32_e32 v142, 16, v134
	v_and_b32_e32 v143, 0xffff0000, v134
	v_lshlrev_b32_e32 v134, 16, v135
	v_and_b32_e32 v135, 0xffff0000, v135
	v_pk_add_f32 v[126:127], v[126:127], v[132:133]
	v_pk_add_f32 v[132:133], v[124:125], v[140:141]
	v_pk_add_f32 v[134:135], v[122:123], v[134:135]
	v_pk_add_f32 v[140:141], v[120:121], v[142:143]
	v_cvt_pk_bf16_f32 v120, v132, v133
	v_cvt_pk_bf16_f32 v121, v126, v127
	v_mul_f32_e32 v133, v133, v133
	v_cvt_pk_bf16_f32 v122, v140, v141
	v_cvt_pk_bf16_f32 v123, v134, v135
	global_store_dwordx4 v[136:137], v[120:123], off sc1
	s_nop 0
	v_mul_f32_e32 v126, v126, v126
	v_mul_f32_e32 v139, v140, v140
	v_fmac_f32_e32 v133, v132, v132
	v_fmac_f32_e32 v126, v127, v127
	v_mul_f32_e32 v134, v134, v134
	v_fmac_f32_e32 v139, v141, v141
	v_add_f32_e32 v126, v133, v126
	v_fmac_f32_e32 v134, v135, v135
	v_add_f32_e32 v126, v139, v126
	v_add_f32_e32 v134, v134, v126
	v_mbcnt_lo_u32_b32 v120, -1, 0
	v_mbcnt_hi_u32_b32 v121, -1, v120
	v_and_b32_e32 v138, 64, v121
	v_xor_b32_e32 v120, 16, v121
	v_add_u32_e32 v138, 64, v138
	v_cmp_lt_i32_e64 s[0:1], v120, v138
	s_waitcnt vmcnt(15)
	v_mov_b64_e32 v[122:123], v[160:161]
	v_mov_b64_e32 v[124:125], v[162:163]
	v_lshlrev_b32_e32 v126, 16, v122
	v_and_b32_e32 v127, 0xffff0000, v122
	v_lshlrev_b32_e32 v122, 16, v123
	v_and_b32_e32 v123, 0xffff0000, v123
	v_lshlrev_b32_e32 v132, 16, v124
	v_and_b32_e32 v133, 0xffff0000, v124
	v_lshlrev_b32_e32 v124, 16, v125
	v_and_b32_e32 v125, 0xffff0000, v125
	v_pk_add_f32 v[118:119], v[118:119], v[122:123]
	v_pk_add_f32 v[116:117], v[116:117], v[126:127]
	v_pk_add_f32 v[122:123], v[114:115], v[124:125]
	v_pk_add_f32 v[124:125], v[112:113], v[132:133]
	v_mul_f32_e32 v112, v117, v117
	v_mul_f32_e32 v113, v118, v118
	v_mul_f32_e32 v114, v124, v124
	v_fmac_f32_e32 v112, v116, v116
	v_fmac_f32_e32 v113, v119, v119
	v_mul_f32_e32 v115, v122, v122
	v_fmac_f32_e32 v114, v125, v125
	v_add_f32_e32 v112, v112, v113
	v_fmac_f32_e32 v115, v123, v123
	v_add_f32_e32 v112, v114, v112
	v_cndmask_b32_e64 v120, v121, v120, s[0:1]
	v_add_f32_e32 v112, v115, v112
	v_lshlrev_b32_e32 v120, 2, v120
	v_add_f32_e32 v112, v134, v112
	ds_bpermute_b32 v113, v120, v112
	v_xor_b32_e32 v114, 32, v121
	v_cmp_lt_i32_e64 s[0:1], v114, v138
	v_cvt_pk_bf16_f32 v116, v116, v117
	v_cvt_pk_bf16_f32 v117, v118, v119
	s_waitcnt lgkmcnt(0)
	v_add_f32_e32 v113, v112, v113
	v_cvt_pk_bf16_f32 v118, v124, v125
	v_cvt_pk_bf16_f32 v119, v122, v123
	v_cndmask_b32_e64 v114, v121, v114, s[0:1]
	v_lshlrev_b32_e32 v112, 2, v114
	ds_bpermute_b32 v114, v112, v113
	global_store_dwordx4 v[136:137], v[116:119], off offset:256 sc1
	s_and_saveexec_b64 s[0:1], vcc
	s_cbranch_execz .LBB0_594
	v_lshl_add_u32 v115, v150, 4, s2
	s_waitcnt lgkmcnt(0)
	v_add_f32_e32 v113, v113, v114
	ds_write_b32 v115, v113
.LBB0_594:
	s_or_b64 exec, exec, s[0:1]
	v_or_b32_e32 v113, 16, v150
	s_waitcnt lgkmcnt(0)
	v_add_u32_e32 v114, s9, v113
	v_ashrrev_i32_e32 v115, 31, v114
	v_lshlrev_b64 v[114:115], 11, v[114:115]
	v_lshl_add_u64 v[114:115], v[114:115], 0, v[130:131]
	v_lshlrev_b64 v[118:119], 1, v[114:115]
	v_lshl_add_u64 v[122:123], s[90:91], 0, v[118:119]
	s_nop 0
	v_lshl_add_u64 v[118:119], s[4:5], 0, v[118:119]
	s_waitcnt vmcnt(15)
	v_mov_b64_e32 v[114:115], v[164:165]
	v_mov_b64_e32 v[116:117], v[166:167]
	v_lshlrev_b32_e32 v124, 16, v114
	v_and_b32_e32 v125, 0xffff0000, v114
	v_lshlrev_b32_e32 v114, 16, v115
	v_and_b32_e32 v115, 0xffff0000, v115
	v_lshlrev_b32_e32 v126, 16, v116
	v_and_b32_e32 v127, 0xffff0000, v116
	v_lshlrev_b32_e32 v116, 16, v117
	v_and_b32_e32 v117, 0xffff0000, v117
	v_pk_add_f32 v[110:111], v[110:111], v[114:115]
	v_pk_add_f32 v[108:109], v[108:109], v[124:125]
	v_pk_add_f32 v[114:115], v[106:107], v[116:117]
	v_pk_add_f32 v[116:117], v[104:105], v[126:127]
	v_cvt_pk_bf16_f32 v104, v108, v109
	v_cvt_pk_bf16_f32 v105, v110, v111
	v_mul_f32_e32 v109, v109, v109
	v_cvt_pk_bf16_f32 v106, v116, v117
	v_cvt_pk_bf16_f32 v107, v114, v115
	global_store_dwordx4 v[118:119], v[104:107], off sc1
	s_nop 0
	v_mul_f32_e32 v110, v110, v110
	v_mul_f32_e32 v116, v116, v116
	v_fmac_f32_e32 v109, v108, v108
	v_fmac_f32_e32 v110, v111, v111
	v_mul_f32_e32 v114, v114, v114
	v_fmac_f32_e32 v116, v117, v117
	v_add_f32_e32 v108, v109, v110
	v_fmac_f32_e32 v114, v115, v115
	v_add_f32_e32 v108, v116, v108
	v_add_f32_e32 v114, v114, v108
	s_waitcnt vmcnt(15)
	v_mov_b64_e32 v[104:105], v[168:169]
	v_mov_b64_e32 v[106:107], v[170:171]
	v_lshlrev_b32_e32 v108, 16, v104
	v_and_b32_e32 v109, 0xffff0000, v104
	v_lshlrev_b32_e32 v104, 16, v105
	v_and_b32_e32 v105, 0xffff0000, v105
	v_lshlrev_b32_e32 v110, 16, v106
	v_and_b32_e32 v111, 0xffff0000, v106
	v_lshlrev_b32_e32 v106, 16, v107
	v_and_b32_e32 v107, 0xffff0000, v107
	v_pk_add_f32 v[102:103], v[102:103], v[104:105]
	v_pk_add_f32 v[100:101], v[100:101], v[108:109]
	v_pk_add_f32 v[104:105], v[98:99], v[106:107]
	v_pk_add_f32 v[106:107], v[96:97], v[110:111]
	v_mul_f32_e32 v96, v101, v101
	v_mul_f32_e32 v97, v102, v102
	v_mul_f32_e32 v98, v106, v106
	v_fmac_f32_e32 v96, v100, v100
	v_fmac_f32_e32 v97, v103, v103
	v_mul_f32_e32 v99, v104, v104
	v_fmac_f32_e32 v98, v107, v107
	v_add_f32_e32 v96, v96, v97
	v_add_f32_e32 v96, v98, v96
	v_fmac_f32_e32 v99, v105, v105
	v_add_f32_e32 v96, v99, v96
	v_add_f32_e32 v96, v114, v96
	ds_bpermute_b32 v97, v120, v96
	v_cvt_pk_bf16_f32 v98, v100, v101
	v_cvt_pk_bf16_f32 v99, v102, v103
	v_cvt_pk_bf16_f32 v100, v106, v107
	v_cvt_pk_bf16_f32 v101, v104, v105
	s_waitcnt lgkmcnt(0)
	v_add_f32_e32 v96, v96, v97
	ds_bpermute_b32 v97, v112, v96
	global_store_dwordx4 v[118:119], v[98:101], off offset:256 sc1
	s_and_saveexec_b64 s[0:1], vcc
	s_cbranch_execz .LBB0_596
	v_lshl_add_u32 v98, v113, 4, s2
	s_waitcnt lgkmcnt(0)
	v_add_f32_e32 v96, v96, v97
	ds_write_b32 v98, v96
.LBB0_596:
	s_or_b64 exec, exec, s[0:1]
	v_or_b32_e32 v96, 32, v150
	v_add_u32_e32 v98, s9, v96
	v_ashrrev_i32_e32 v99, 31, v98
	v_lshlrev_b64 v[98:99], 11, v[98:99]
	v_lshl_add_u64 v[98:99], v[98:99], 0, v[130:131]
	v_lshlrev_b64 v[102:103], 1, v[98:99]
	v_lshl_add_u64 v[104:105], s[90:91], 0, v[102:103]
	s_nop 0
	v_lshl_add_u64 v[102:103], s[4:5], 0, v[102:103]
	s_waitcnt vmcnt(15)
	v_mov_b64_e32 v[98:99], v[172:173]
	v_mov_b64_e32 v[100:101], v[174:175]
	v_lshlrev_b32_e32 v106, 16, v98
	v_and_b32_e32 v107, 0xffff0000, v98
	v_lshlrev_b32_e32 v98, 16, v99
	v_and_b32_e32 v99, 0xffff0000, v99
	v_lshlrev_b32_e32 v108, 16, v100
	v_and_b32_e32 v109, 0xffff0000, v100
	v_lshlrev_b32_e32 v100, 16, v101
	v_and_b32_e32 v101, 0xffff0000, v101
	v_pk_add_f32 v[94:95], v[94:95], v[98:99]
	v_pk_add_f32 v[92:93], v[92:93], v[106:107]
	v_pk_add_f32 v[98:99], v[90:91], v[100:101]
	v_pk_add_f32 v[100:101], v[88:89], v[108:109]
	v_cvt_pk_bf16_f32 v88, v92, v93
	v_cvt_pk_bf16_f32 v89, v94, v95
	v_mul_f32_e32 v93, v93, v93
	v_cvt_pk_bf16_f32 v90, v100, v101
	v_cvt_pk_bf16_f32 v91, v98, v99
	global_store_dwordx4 v[102:103], v[88:91], off sc1
	s_nop 0
	v_mul_f32_e32 v94, v94, v94
	s_waitcnt lgkmcnt(0)
	v_mul_f32_e32 v97, v100, v100
	v_fmac_f32_e32 v93, v92, v92
	v_fmac_f32_e32 v94, v95, v95
	v_mul_f32_e32 v98, v98, v98
	v_fmac_f32_e32 v97, v101, v101
	v_add_f32_e32 v92, v93, v94
	v_fmac_f32_e32 v98, v99, v99
	v_add_f32_e32 v92, v97, v92
	v_add_f32_e32 v97, v98, v92
	s_waitcnt vmcnt(15)
	v_mov_b64_e32 v[88:89], v[176:177]
	v_mov_b64_e32 v[90:91], v[178:179]
	v_lshlrev_b32_e32 v92, 16, v88
	v_and_b32_e32 v93, 0xffff0000, v88
	v_lshlrev_b32_e32 v88, 16, v89
	v_and_b32_e32 v89, 0xffff0000, v89
	v_lshlrev_b32_e32 v94, 16, v90
	v_and_b32_e32 v95, 0xffff0000, v90
	v_lshlrev_b32_e32 v90, 16, v91
	v_and_b32_e32 v91, 0xffff0000, v91
	v_pk_add_f32 v[86:87], v[86:87], v[88:89]
	v_pk_add_f32 v[84:85], v[84:85], v[92:93]
	v_pk_add_f32 v[88:89], v[82:83], v[90:91]
	v_pk_add_f32 v[90:91], v[80:81], v[94:95]
	v_mul_f32_e32 v80, v85, v85
	v_mul_f32_e32 v81, v86, v86
	v_mul_f32_e32 v82, v90, v90
	v_fmac_f32_e32 v80, v84, v84
	v_fmac_f32_e32 v81, v87, v87
	v_mul_f32_e32 v83, v88, v88
	v_fmac_f32_e32 v82, v91, v91
	v_add_f32_e32 v80, v80, v81
	v_add_f32_e32 v80, v82, v80
	v_fmac_f32_e32 v83, v89, v89
	v_add_f32_e32 v80, v83, v80
	v_add_f32_e32 v80, v97, v80
	ds_bpermute_b32 v81, v120, v80
	v_cvt_pk_bf16_f32 v82, v84, v85
	v_cvt_pk_bf16_f32 v83, v86, v87
	v_cvt_pk_bf16_f32 v84, v90, v91
	v_cvt_pk_bf16_f32 v85, v88, v89
	s_waitcnt lgkmcnt(0)
	v_add_f32_e32 v80, v80, v81
	ds_bpermute_b32 v81, v112, v80
	global_store_dwordx4 v[102:103], v[82:85], off offset:256 sc1
	s_and_saveexec_b64 s[0:1], vcc
	s_cbranch_execz .LBB0_598
	v_lshl_add_u32 v82, v96, 4, s2
	s_waitcnt lgkmcnt(0)
	v_add_f32_e32 v80, v80, v81
	ds_write_b32 v82, v80
.LBB0_598:
	s_or_b64 exec, exec, s[0:1]
	v_or_b32_e32 v80, 48, v150
	v_add_u32_e32 v82, s9, v80
	v_ashrrev_i32_e32 v83, 31, v82
	v_lshlrev_b64 v[82:83], 11, v[82:83]
	v_lshl_add_u64 v[82:83], v[82:83], 0, v[130:131]
	v_lshlrev_b64 v[86:87], 1, v[82:83]
	v_lshl_add_u64 v[88:89], s[90:91], 0, v[86:87]
	s_nop 0
	v_lshl_add_u64 v[86:87], s[4:5], 0, v[86:87]
	s_waitcnt vmcnt(15)
	v_mov_b64_e32 v[82:83], v[180:181]
	v_mov_b64_e32 v[84:85], v[182:183]
	v_lshlrev_b32_e32 v90, 16, v82
	v_and_b32_e32 v91, 0xffff0000, v82
	v_lshlrev_b32_e32 v82, 16, v83
	v_and_b32_e32 v83, 0xffff0000, v83
	v_lshlrev_b32_e32 v92, 16, v84
	v_and_b32_e32 v93, 0xffff0000, v84
	v_lshlrev_b32_e32 v84, 16, v85
	v_and_b32_e32 v85, 0xffff0000, v85
	v_pk_add_f32 v[78:79], v[78:79], v[82:83]
	v_pk_add_f32 v[76:77], v[76:77], v[90:91]
	v_pk_add_f32 v[82:83], v[74:75], v[84:85]
	v_pk_add_f32 v[84:85], v[72:73], v[92:93]
	v_cvt_pk_bf16_f32 v72, v76, v77
	v_cvt_pk_bf16_f32 v73, v78, v79
	v_mul_f32_e32 v77, v77, v77
	v_cvt_pk_bf16_f32 v74, v84, v85
	v_cvt_pk_bf16_f32 v75, v82, v83
	global_store_dwordx4 v[86:87], v[72:75], off sc1
	s_nop 0
	v_mul_f32_e32 v78, v78, v78
	s_waitcnt lgkmcnt(0)
	v_mul_f32_e32 v81, v84, v84
	v_fmac_f32_e32 v77, v76, v76
	v_fmac_f32_e32 v78, v79, v79
	v_mul_f32_e32 v82, v82, v82
	v_fmac_f32_e32 v81, v85, v85
	v_add_f32_e32 v76, v77, v78
	v_fmac_f32_e32 v82, v83, v83
	v_add_f32_e32 v76, v81, v76
	v_add_f32_e32 v81, v82, v76
	s_waitcnt vmcnt(15)
	v_mov_b64_e32 v[72:73], v[184:185]
	v_mov_b64_e32 v[74:75], v[186:187]
	v_lshlrev_b32_e32 v76, 16, v72
	v_and_b32_e32 v77, 0xffff0000, v72
	v_lshlrev_b32_e32 v72, 16, v73
	v_and_b32_e32 v73, 0xffff0000, v73
	v_lshlrev_b32_e32 v78, 16, v74
	v_and_b32_e32 v79, 0xffff0000, v74
	v_lshlrev_b32_e32 v74, 16, v75
	v_and_b32_e32 v75, 0xffff0000, v75
	v_pk_add_f32 v[70:71], v[70:71], v[72:73]
	v_pk_add_f32 v[68:69], v[68:69], v[76:77]
	v_pk_add_f32 v[72:73], v[66:67], v[74:75]
	v_pk_add_f32 v[74:75], v[64:65], v[78:79]
	v_mul_f32_e32 v64, v69, v69
	v_mul_f32_e32 v65, v70, v70
	v_mul_f32_e32 v66, v74, v74
	v_fmac_f32_e32 v64, v68, v68
	v_fmac_f32_e32 v65, v71, v71
	v_mul_f32_e32 v67, v72, v72
	v_fmac_f32_e32 v66, v75, v75
	v_add_f32_e32 v64, v64, v65
	v_add_f32_e32 v64, v66, v64
	v_fmac_f32_e32 v67, v73, v73
	v_add_f32_e32 v64, v67, v64
	v_add_f32_e32 v64, v81, v64
	ds_bpermute_b32 v65, v120, v64
	v_cvt_pk_bf16_f32 v66, v68, v69
	v_cvt_pk_bf16_f32 v67, v70, v71
	v_cvt_pk_bf16_f32 v68, v74, v75
	v_cvt_pk_bf16_f32 v69, v72, v73
	s_waitcnt lgkmcnt(0)
	v_add_f32_e32 v64, v64, v65
	ds_bpermute_b32 v65, v112, v64
	global_store_dwordx4 v[86:87], v[66:69], off offset:256 sc1
	s_and_saveexec_b64 s[0:1], vcc
	s_cbranch_execz .LBB0_600
	v_lshl_add_u32 v66, v80, 4, s2
	s_waitcnt lgkmcnt(0)
	v_add_f32_e32 v64, v64, v65
	ds_write_b32 v66, v64
.LBB0_600:
	s_or_b64 exec, exec, s[0:1]
	v_add_u32_e32 v64, 0x80, v150
	v_add_u32_e32 v66, s9, v64
	v_ashrrev_i32_e32 v67, 31, v66
	v_lshlrev_b64 v[66:67], 11, v[66:67]
	v_lshl_add_u64 v[66:67], v[66:67], 0, v[130:131]
	v_lshlrev_b64 v[70:71], 1, v[66:67]
	v_lshl_add_u64 v[72:73], s[90:91], 0, v[70:71]
	s_nop 0
	v_lshl_add_u64 v[70:71], s[4:5], 0, v[70:71]
	s_waitcnt vmcnt(15)
	v_mov_b64_e32 v[66:67], v[188:189]
	v_mov_b64_e32 v[68:69], v[190:191]
	v_lshlrev_b32_e32 v74, 16, v66
	v_and_b32_e32 v75, 0xffff0000, v66
	v_lshlrev_b32_e32 v66, 16, v67
	v_and_b32_e32 v67, 0xffff0000, v67
	v_lshlrev_b32_e32 v76, 16, v68
	v_and_b32_e32 v77, 0xffff0000, v68
	v_lshlrev_b32_e32 v68, 16, v69
	v_and_b32_e32 v69, 0xffff0000, v69
	v_pk_add_f32 v[62:63], v[62:63], v[66:67]
	v_pk_add_f32 v[60:61], v[60:61], v[74:75]
	v_pk_add_f32 v[66:67], v[58:59], v[68:69]
	v_pk_add_f32 v[68:69], v[56:57], v[76:77]
	v_cvt_pk_bf16_f32 v56, v60, v61
	v_cvt_pk_bf16_f32 v57, v62, v63
	v_mul_f32_e32 v61, v61, v61
	v_cvt_pk_bf16_f32 v58, v68, v69
	v_cvt_pk_bf16_f32 v59, v66, v67
	global_store_dwordx4 v[70:71], v[56:59], off sc1
	s_nop 0
	v_mul_f32_e32 v62, v62, v62
	s_waitcnt lgkmcnt(0)
	v_mul_f32_e32 v65, v68, v68
	v_fmac_f32_e32 v61, v60, v60
	v_fmac_f32_e32 v62, v63, v63
	v_mul_f32_e32 v66, v66, v66
	v_fmac_f32_e32 v65, v69, v69
	v_add_f32_e32 v60, v61, v62
	v_fmac_f32_e32 v66, v67, v67
	v_add_f32_e32 v60, v65, v60
	v_add_f32_e32 v65, v66, v60
	s_waitcnt vmcnt(15)
	v_mov_b64_e32 v[56:57], v[192:193]
	v_mov_b64_e32 v[58:59], v[194:195]
	v_lshlrev_b32_e32 v60, 16, v56
	v_and_b32_e32 v61, 0xffff0000, v56
	v_lshlrev_b32_e32 v56, 16, v57
	v_and_b32_e32 v57, 0xffff0000, v57
	v_lshlrev_b32_e32 v62, 16, v58
	v_and_b32_e32 v63, 0xffff0000, v58
	v_lshlrev_b32_e32 v58, 16, v59
	v_and_b32_e32 v59, 0xffff0000, v59
	v_pk_add_f32 v[54:55], v[54:55], v[56:57]
	v_pk_add_f32 v[52:53], v[52:53], v[60:61]
	v_pk_add_f32 v[56:57], v[50:51], v[58:59]
	v_pk_add_f32 v[58:59], v[48:49], v[62:63]
	v_mul_f32_e32 v48, v53, v53
	v_mul_f32_e32 v49, v54, v54
	v_mul_f32_e32 v50, v58, v58
	v_fmac_f32_e32 v48, v52, v52
	v_fmac_f32_e32 v49, v55, v55
	v_mul_f32_e32 v51, v56, v56
	v_fmac_f32_e32 v50, v59, v59
	v_add_f32_e32 v48, v48, v49
	v_add_f32_e32 v48, v50, v48
	v_fmac_f32_e32 v51, v57, v57
	v_add_f32_e32 v48, v51, v48
	v_add_f32_e32 v48, v65, v48
	ds_bpermute_b32 v49, v120, v48
	v_cvt_pk_bf16_f32 v50, v52, v53
	v_cvt_pk_bf16_f32 v51, v54, v55
	v_cvt_pk_bf16_f32 v52, v58, v59
	v_cvt_pk_bf16_f32 v53, v56, v57
	s_waitcnt lgkmcnt(0)
	v_add_f32_e32 v48, v48, v49
	ds_bpermute_b32 v49, v112, v48
	global_store_dwordx4 v[70:71], v[50:53], off offset:256 sc1
	s_and_saveexec_b64 s[0:1], vcc
	s_cbranch_execz .LBB0_602
	v_lshl_add_u32 v50, v64, 4, s2
	s_waitcnt lgkmcnt(0)
	v_add_f32_e32 v48, v48, v49
	ds_write_b32 v50, v48
.LBB0_602:
	s_or_b64 exec, exec, s[0:1]
	v_add_u32_e32 v48, 0x90, v150
	v_add_u32_e32 v50, s9, v48
	v_ashrrev_i32_e32 v51, 31, v50
	v_lshlrev_b64 v[50:51], 11, v[50:51]
	v_lshl_add_u64 v[50:51], v[50:51], 0, v[130:131]
	v_lshlrev_b64 v[54:55], 1, v[50:51]
	v_lshl_add_u64 v[56:57], s[90:91], 0, v[54:55]
	s_nop 0
	v_lshl_add_u64 v[54:55], s[4:5], 0, v[54:55]
	s_waitcnt vmcnt(15)
	v_mov_b64_e32 v[50:51], v[196:197]
	v_mov_b64_e32 v[52:53], v[198:199]
	v_lshlrev_b32_e32 v58, 16, v50
	v_and_b32_e32 v59, 0xffff0000, v50
	v_lshlrev_b32_e32 v50, 16, v51
	v_and_b32_e32 v51, 0xffff0000, v51
	v_lshlrev_b32_e32 v60, 16, v52
	v_and_b32_e32 v61, 0xffff0000, v52
	v_lshlrev_b32_e32 v52, 16, v53
	v_and_b32_e32 v53, 0xffff0000, v53
	v_pk_add_f32 v[46:47], v[46:47], v[50:51]
	v_pk_add_f32 v[44:45], v[44:45], v[58:59]
	v_pk_add_f32 v[50:51], v[42:43], v[52:53]
	v_pk_add_f32 v[52:53], v[40:41], v[60:61]
	v_cvt_pk_bf16_f32 v40, v44, v45
	v_cvt_pk_bf16_f32 v41, v46, v47
	v_mul_f32_e32 v45, v45, v45
	v_cvt_pk_bf16_f32 v42, v52, v53
	v_cvt_pk_bf16_f32 v43, v50, v51
	global_store_dwordx4 v[54:55], v[40:43], off sc1
	s_nop 0
	v_mul_f32_e32 v46, v46, v46
	s_waitcnt lgkmcnt(0)
	v_mul_f32_e32 v49, v52, v52
	v_fmac_f32_e32 v45, v44, v44
	v_fmac_f32_e32 v46, v47, v47
	v_mul_f32_e32 v50, v50, v50
	v_fmac_f32_e32 v49, v53, v53
	v_add_f32_e32 v44, v45, v46
	v_fmac_f32_e32 v50, v51, v51
	v_add_f32_e32 v44, v49, v44
	v_add_f32_e32 v49, v50, v44
	s_waitcnt vmcnt(15)
	v_mov_b64_e32 v[40:41], v[200:201]
	v_mov_b64_e32 v[42:43], v[202:203]
	v_lshlrev_b32_e32 v44, 16, v40
	v_and_b32_e32 v45, 0xffff0000, v40
	v_lshlrev_b32_e32 v40, 16, v41
	v_and_b32_e32 v41, 0xffff0000, v41
	v_lshlrev_b32_e32 v46, 16, v42
	v_and_b32_e32 v47, 0xffff0000, v42
	v_lshlrev_b32_e32 v42, 16, v43
	v_and_b32_e32 v43, 0xffff0000, v43
	v_pk_add_f32 v[38:39], v[38:39], v[40:41]
	v_pk_add_f32 v[36:37], v[36:37], v[44:45]
	v_pk_add_f32 v[40:41], v[34:35], v[42:43]
	v_pk_add_f32 v[42:43], v[32:33], v[46:47]
	v_mul_f32_e32 v32, v37, v37
	v_mul_f32_e32 v33, v38, v38
	v_mul_f32_e32 v34, v42, v42
	v_fmac_f32_e32 v32, v36, v36
	v_fmac_f32_e32 v33, v39, v39
	v_mul_f32_e32 v35, v40, v40
	v_fmac_f32_e32 v34, v43, v43
	v_add_f32_e32 v32, v32, v33
	v_add_f32_e32 v32, v34, v32
	v_fmac_f32_e32 v35, v41, v41
	v_add_f32_e32 v32, v35, v32
	v_add_f32_e32 v32, v49, v32
	ds_bpermute_b32 v33, v120, v32
	v_cvt_pk_bf16_f32 v34, v36, v37
	v_cvt_pk_bf16_f32 v35, v38, v39
	v_cvt_pk_bf16_f32 v36, v42, v43
	v_cvt_pk_bf16_f32 v37, v40, v41
	s_waitcnt lgkmcnt(0)
	v_add_f32_e32 v32, v32, v33
	ds_bpermute_b32 v33, v112, v32
	global_store_dwordx4 v[54:55], v[34:37], off offset:256 sc1
	s_and_saveexec_b64 s[0:1], vcc
	s_cbranch_execz .LBB0_604
	v_lshl_add_u32 v34, v48, 4, s2
	s_waitcnt lgkmcnt(0)
	v_add_f32_e32 v32, v32, v33
	ds_write_b32 v34, v32
.LBB0_604:
	s_or_b64 exec, exec, s[0:1]
	v_add_u32_e32 v32, 0xa0, v150
	v_add_u32_e32 v34, s9, v32
	v_ashrrev_i32_e32 v35, 31, v34
	v_lshlrev_b64 v[34:35], 11, v[34:35]
	v_lshl_add_u64 v[34:35], v[34:35], 0, v[130:131]
	v_lshlrev_b64 v[38:39], 1, v[34:35]
	v_lshl_add_u64 v[40:41], s[90:91], 0, v[38:39]
	s_nop 0
	v_lshl_add_u64 v[38:39], s[4:5], 0, v[38:39]
	s_waitcnt vmcnt(15)
	v_mov_b64_e32 v[34:35], v[204:205]
	v_mov_b64_e32 v[36:37], v[206:207]
	v_lshlrev_b32_e32 v42, 16, v34
	v_and_b32_e32 v43, 0xffff0000, v34
	v_lshlrev_b32_e32 v34, 16, v35
	v_and_b32_e32 v35, 0xffff0000, v35
	v_lshlrev_b32_e32 v44, 16, v36
	v_and_b32_e32 v45, 0xffff0000, v36
	v_lshlrev_b32_e32 v36, 16, v37
	v_and_b32_e32 v37, 0xffff0000, v37
	v_pk_add_f32 v[30:31], v[30:31], v[34:35]
	v_pk_add_f32 v[28:29], v[28:29], v[42:43]
	v_pk_add_f32 v[34:35], v[26:27], v[36:37]
	v_pk_add_f32 v[36:37], v[24:25], v[44:45]
	v_cvt_pk_bf16_f32 v24, v28, v29
	v_cvt_pk_bf16_f32 v25, v30, v31
	v_mul_f32_e32 v29, v29, v29
	v_cvt_pk_bf16_f32 v26, v36, v37
	v_cvt_pk_bf16_f32 v27, v34, v35
	global_store_dwordx4 v[38:39], v[24:27], off sc1
	s_nop 0
	v_mul_f32_e32 v30, v30, v30
	s_waitcnt lgkmcnt(0)
	v_mul_f32_e32 v33, v36, v36
	v_fmac_f32_e32 v29, v28, v28
	v_fmac_f32_e32 v30, v31, v31
	v_mul_f32_e32 v34, v34, v34
	v_fmac_f32_e32 v33, v37, v37
	v_add_f32_e32 v28, v29, v30
	v_fmac_f32_e32 v34, v35, v35
	v_add_f32_e32 v28, v33, v28
	v_add_f32_e32 v33, v34, v28
	s_waitcnt vmcnt(15)
	v_mov_b64_e32 v[24:25], v[208:209]
	v_mov_b64_e32 v[26:27], v[210:211]
	v_lshlrev_b32_e32 v28, 16, v24
	v_and_b32_e32 v29, 0xffff0000, v24
	v_lshlrev_b32_e32 v24, 16, v25
	v_and_b32_e32 v25, 0xffff0000, v25
	v_lshlrev_b32_e32 v30, 16, v26
	v_and_b32_e32 v31, 0xffff0000, v26
	v_lshlrev_b32_e32 v26, 16, v27
	v_and_b32_e32 v27, 0xffff0000, v27
	v_pk_add_f32 v[22:23], v[22:23], v[24:25]
	v_pk_add_f32 v[20:21], v[20:21], v[28:29]
	v_pk_add_f32 v[24:25], v[18:19], v[26:27]
	v_pk_add_f32 v[26:27], v[16:17], v[30:31]
	v_mul_f32_e32 v16, v21, v21
	v_mul_f32_e32 v17, v22, v22
	v_mul_f32_e32 v18, v26, v26
	v_fmac_f32_e32 v16, v20, v20
	v_fmac_f32_e32 v17, v23, v23
	v_mul_f32_e32 v19, v24, v24
	v_fmac_f32_e32 v18, v27, v27
	v_add_f32_e32 v16, v16, v17
	v_add_f32_e32 v16, v18, v16
	v_fmac_f32_e32 v19, v25, v25
	v_add_f32_e32 v16, v19, v16
	v_add_f32_e32 v16, v33, v16
	ds_bpermute_b32 v17, v120, v16
	v_cvt_pk_bf16_f32 v18, v20, v21
	v_cvt_pk_bf16_f32 v19, v22, v23
	v_cvt_pk_bf16_f32 v20, v26, v27
	v_cvt_pk_bf16_f32 v21, v24, v25
	s_waitcnt lgkmcnt(0)
	v_add_f32_e32 v16, v16, v17
	ds_bpermute_b32 v17, v112, v16
	global_store_dwordx4 v[38:39], v[18:21], off offset:256 sc1
	s_and_saveexec_b64 s[0:1], vcc
	s_cbranch_execz .LBB0_606
	v_lshl_add_u32 v18, v32, 4, s2
	s_waitcnt lgkmcnt(0)
	v_add_f32_e32 v16, v16, v17
	ds_write_b32 v18, v16
.LBB0_606:
	s_or_b64 exec, exec, s[0:1]
	v_add_u32_e32 v16, 0xb0, v150
	v_add_u32_e32 v18, s9, v16
	v_ashrrev_i32_e32 v19, 31, v18
	v_lshlrev_b64 v[18:19], 11, v[18:19]
	v_lshl_add_u64 v[18:19], v[18:19], 0, v[130:131]
	v_lshlrev_b64 v[22:23], 1, v[18:19]
	v_lshl_add_u64 v[24:25], s[90:91], 0, v[22:23]
	s_nop 0
	v_lshl_add_u64 v[22:23], s[4:5], 0, v[22:23]
	s_waitcnt vmcnt(15)
	v_mov_b64_e32 v[18:19], v[212:213]
	v_mov_b64_e32 v[20:21], v[214:215]
	v_lshlrev_b32_e32 v26, 16, v18
	v_and_b32_e32 v27, 0xffff0000, v18
	v_lshlrev_b32_e32 v18, 16, v19
	v_and_b32_e32 v19, 0xffff0000, v19
	v_lshlrev_b32_e32 v28, 16, v20
	v_and_b32_e32 v29, 0xffff0000, v20
	v_lshlrev_b32_e32 v20, 16, v21
	v_and_b32_e32 v21, 0xffff0000, v21
	v_pk_add_f32 v[14:15], v[14:15], v[18:19]
	v_pk_add_f32 v[12:13], v[12:13], v[26:27]
	v_pk_add_f32 v[18:19], v[10:11], v[20:21]
	v_pk_add_f32 v[20:21], v[8:9], v[28:29]
	v_cvt_pk_bf16_f32 v8, v12, v13
	v_cvt_pk_bf16_f32 v9, v14, v15
	v_mul_f32_e32 v13, v13, v13
	v_cvt_pk_bf16_f32 v10, v20, v21
	v_cvt_pk_bf16_f32 v11, v18, v19
	global_store_dwordx4 v[22:23], v[8:11], off sc1
	s_nop 0
	v_mul_f32_e32 v14, v14, v14
	s_waitcnt lgkmcnt(0)
	v_mul_f32_e32 v17, v20, v20
	v_fmac_f32_e32 v13, v12, v12
	v_fmac_f32_e32 v14, v15, v15
	v_mul_f32_e32 v18, v18, v18
	v_fmac_f32_e32 v17, v21, v21
	v_add_f32_e32 v12, v13, v14
	v_fmac_f32_e32 v18, v19, v19
	v_add_f32_e32 v12, v17, v12
	v_add_f32_e32 v17, v18, v12
	s_waitcnt vmcnt(15)
	v_mov_b64_e32 v[8:9], v[216:217]
	v_mov_b64_e32 v[10:11], v[218:219]
	v_lshlrev_b32_e32 v12, 16, v8
	v_and_b32_e32 v13, 0xffff0000, v8
	v_lshlrev_b32_e32 v8, 16, v9
	v_and_b32_e32 v9, 0xffff0000, v9
	v_lshlrev_b32_e32 v14, 16, v10
	v_and_b32_e32 v15, 0xffff0000, v10
	v_lshlrev_b32_e32 v10, 16, v11
	v_and_b32_e32 v11, 0xffff0000, v11
	v_pk_add_f32 v[6:7], v[6:7], v[8:9]
	v_pk_add_f32 v[4:5], v[4:5], v[12:13]
	v_pk_add_f32 v[8:9], v[2:3], v[10:11]
	v_pk_add_f32 v[10:11], v[0:1], v[14:15]
	v_mul_f32_e32 v0, v5, v5
	v_mul_f32_e32 v1, v6, v6
	v_mul_f32_e32 v2, v10, v10
	v_fmac_f32_e32 v0, v4, v4
	v_fmac_f32_e32 v1, v7, v7
	v_mul_f32_e32 v3, v8, v8
	v_fmac_f32_e32 v2, v11, v11
	v_add_f32_e32 v0, v0, v1
	v_add_f32_e32 v0, v2, v0
	v_fmac_f32_e32 v3, v9, v9
	v_add_f32_e32 v0, v3, v0
	v_add_f32_e32 v0, v17, v0
	ds_bpermute_b32 v1, v120, v0
	v_cvt_pk_bf16_f32 v2, v4, v5
	v_cvt_pk_bf16_f32 v3, v6, v7
	v_cvt_pk_bf16_f32 v4, v10, v11
	v_cvt_pk_bf16_f32 v5, v8, v9
	s_waitcnt lgkmcnt(0)
	v_add_f32_e32 v0, v0, v1
	ds_bpermute_b32 v1, v112, v0
	global_store_dwordx4 v[22:23], v[2:5], off offset:256 sc1
	s_and_saveexec_b64 s[0:1], vcc
	s_cbranch_execz .LBB0_608
	v_lshl_add_u32 v2, v16, 4, s2
	s_waitcnt lgkmcnt(0)
	v_add_f32_e32 v0, v0, v1
	ds_write_b32 v2, v0

.LBB0_674:
	s_andn2_b64 vcc, exec, s[0:1]
	s_mov_b64 s[0:1], -1
	s_waitcnt vmcnt(14)
	v_add_f32_e32 v156, v156, v157
	v_add_f32_e32 v158, v158, v159
	v_add_f32_e32 v160, v160, v161
	v_add_f32_e32 v162, v162, v163
	v_add_f32_e32 v156, v156, v158
	v_add_f32_e32 v160, v160, v162
	v_add_f32_e32 v156, v156, v160
	v_fmamk_f32 v156, v156, 0x3a000000, v154
	v_rsq_f32_e32 v146, v156
	v_mov_b32_e32 v147, v155
	v_pk_mul_f32 v[116:117], v[116:117], v[146:147] op_sel_hi:[1,0]
	v_pk_mul_f32 v[118:119], v[118:119], v[146:147] op_sel_hi:[1,0]
	v_pk_mul_f32 v[112:113], v[112:113], v[146:147] op_sel_hi:[1,0]
	v_pk_mul_f32 v[114:115], v[114:115], v[146:147] op_sel_hi:[1,0]
	v_pk_mul_f32 v[124:125], v[124:125], v[146:147] op_sel_hi:[1,0]
	v_pk_mul_f32 v[126:127], v[126:127], v[146:147] op_sel_hi:[1,0]
	v_pk_mul_f32 v[120:121], v[120:121], v[146:147] op_sel_hi:[1,0]
	v_pk_mul_f32 v[122:123], v[122:123], v[146:147] op_sel_hi:[1,0]
	v_pk_mul_f32 v[156:157], v[116:117], v[252:253] op_sel_hi:[1,0]
	v_pk_mul_f32 v[158:159], v[118:119], v[252:253] op_sel_hi:[1,0]
	v_pk_mul_f32 v[160:161], v[112:113], v[252:253] op_sel_hi:[1,0]
	v_pk_mul_f32 v[162:163], v[114:115], v[252:253] op_sel_hi:[1,0]
	v_exp_f32_e32 v156, v156
	v_exp_f32_e32 v157, v157
	v_exp_f32_e32 v158, v158
	v_exp_f32_e32 v159, v159
	v_exp_f32_e32 v160, v160
	v_exp_f32_e32 v161, v161
	v_exp_f32_e32 v162, v162
	v_exp_f32_e32 v163, v163
	v_pk_add_f32 v[156:157], v[156:157], v[252:253] op_sel:[0,1]
	v_pk_add_f32 v[158:159], v[158:159], v[252:253] op_sel:[0,1]
	v_pk_add_f32 v[160:161], v[160:161], v[252:253] op_sel:[0,1]
	v_pk_add_f32 v[162:163], v[162:163], v[252:253] op_sel:[0,1]
	v_rcp_f32_e32 v156, v156
	v_rcp_f32_e32 v157, v157
	v_rcp_f32_e32 v158, v158
	v_rcp_f32_e32 v159, v159
	v_rcp_f32_e32 v160, v160
	v_rcp_f32_e32 v161, v161
	v_rcp_f32_e32 v162, v162
	v_rcp_f32_e32 v163, v163
	v_pk_mul_f32 v[116:117], v[116:117], v[156:157]
	v_pk_mul_f32 v[118:119], v[118:119], v[158:159]
	v_pk_mul_f32 v[112:113], v[112:113], v[160:161]
	v_pk_mul_f32 v[114:115], v[114:115], v[162:163]
	v_pk_mul_f32 v[116:117], v[124:125], v[116:117]
	v_pk_mul_f32 v[118:119], v[126:127], v[118:119]
	v_pk_mul_f32 v[112:113], v[120:121], v[112:113]
	v_pk_mul_f32 v[114:115], v[122:123], v[114:115]
	v_cvt_pk_bf16_f32 v120, v116, v117
	v_cvt_pk_bf16_f32 v121, v118, v119
	v_cvt_pk_bf16_f32 v122, v112, v113
	v_cvt_pk_bf16_f32 v123, v114, v115
	global_store_dwordx4 v147, v[120:123], s[8:9] sc1
	s_waitcnt vmcnt(13)
	v_add_f32_e32 v164, v164, v165
	v_add_f32_e32 v166, v166, v167
	v_add_f32_e32 v168, v168, v169
	v_add_f32_e32 v170, v170, v171
	v_add_f32_e32 v164, v164, v166
	v_add_f32_e32 v168, v168, v170
	v_add_f32_e32 v164, v164, v168
	v_fmamk_f32 v164, v164, 0x3a000000, v154
	v_rsq_f32_e32 v146, v164
	v_add_u32_e32 v147, 0x2c000, v155
	v_pk_mul_f32 v[100:101], v[100:101], v[146:147] op_sel_hi:[1,0]
	v_pk_mul_f32 v[102:103], v[102:103], v[146:147] op_sel_hi:[1,0]
	v_pk_mul_f32 v[96:97], v[96:97], v[146:147] op_sel_hi:[1,0]
	v_pk_mul_f32 v[98:99], v[98:99], v[146:147] op_sel_hi:[1,0]
	v_pk_mul_f32 v[108:109], v[108:109], v[146:147] op_sel_hi:[1,0]
	v_pk_mul_f32 v[110:111], v[110:111], v[146:147] op_sel_hi:[1,0]
	v_pk_mul_f32 v[104:105], v[104:105], v[146:147] op_sel_hi:[1,0]
	v_pk_mul_f32 v[106:107], v[106:107], v[146:147] op_sel_hi:[1,0]
	v_pk_mul_f32 v[164:165], v[100:101], v[252:253] op_sel_hi:[1,0]
	v_pk_mul_f32 v[166:167], v[102:103], v[252:253] op_sel_hi:[1,0]
	v_pk_mul_f32 v[168:169], v[96:97], v[252:253] op_sel_hi:[1,0]
	v_pk_mul_f32 v[170:171], v[98:99], v[252:253] op_sel_hi:[1,0]
	v_exp_f32_e32 v164, v164
	v_exp_f32_e32 v165, v165
	v_exp_f32_e32 v166, v166
	v_exp_f32_e32 v167, v167
	v_exp_f32_e32 v168, v168
	v_exp_f32_e32 v169, v169
	v_exp_f32_e32 v170, v170
	v_exp_f32_e32 v171, v171
	v_pk_add_f32 v[164:165], v[164:165], v[252:253] op_sel:[0,1]
	v_pk_add_f32 v[166:167], v[166:167], v[252:253] op_sel:[0,1]
	v_pk_add_f32 v[168:169], v[168:169], v[252:253] op_sel:[0,1]
	v_pk_add_f32 v[170:171], v[170:171], v[252:253] op_sel:[0,1]
	v_rcp_f32_e32 v164, v164
	v_rcp_f32_e32 v165, v165
	v_rcp_f32_e32 v166, v166
	v_rcp_f32_e32 v167, v167
	v_rcp_f32_e32 v168, v168
	v_rcp_f32_e32 v169, v169
	v_rcp_f32_e32 v170, v170
	v_rcp_f32_e32 v171, v171
	v_pk_mul_f32 v[100:101], v[100:101], v[164:165]
	v_pk_mul_f32 v[102:103], v[102:103], v[166:167]
	v_pk_mul_f32 v[96:97], v[96:97], v[168:169]
	v_pk_mul_f32 v[98:99], v[98:99], v[170:171]
	v_pk_mul_f32 v[100:101], v[108:109], v[100:101]
	v_pk_mul_f32 v[102:103], v[110:111], v[102:103]
	v_pk_mul_f32 v[96:97], v[104:105], v[96:97]
	v_pk_mul_f32 v[98:99], v[106:107], v[98:99]
	v_cvt_pk_bf16_f32 v104, v100, v101
	v_cvt_pk_bf16_f32 v105, v102, v103
	v_cvt_pk_bf16_f32 v106, v96, v97
	v_cvt_pk_bf16_f32 v107, v98, v99
	global_store_dwordx4 v147, v[104:107], s[8:9] sc1
	s_waitcnt vmcnt(12)
	v_add_f32_e32 v172, v172, v173
	v_add_f32_e32 v174, v174, v175
	v_add_f32_e32 v176, v176, v177
	v_add_f32_e32 v178, v178, v179
	v_add_f32_e32 v172, v172, v174
	v_add_f32_e32 v176, v176, v178
	v_add_f32_e32 v172, v172, v176
	v_fmamk_f32 v172, v172, 0x3a000000, v154
	v_rsq_f32_e32 v146, v172
	v_add_u32_e32 v147, 0x58000, v155
	v_pk_mul_f32 v[84:85], v[84:85], v[146:147] op_sel_hi:[1,0]
	v_pk_mul_f32 v[86:87], v[86:87], v[146:147] op_sel_hi:[1,0]
	v_pk_mul_f32 v[80:81], v[80:81], v[146:147] op_sel_hi:[1,0]
	v_pk_mul_f32 v[82:83], v[82:83], v[146:147] op_sel_hi:[1,0]
	v_pk_mul_f32 v[92:93], v[92:93], v[146:147] op_sel_hi:[1,0]
	v_pk_mul_f32 v[94:95], v[94:95], v[146:147] op_sel_hi:[1,0]
	v_pk_mul_f32 v[88:89], v[88:89], v[146:147] op_sel_hi:[1,0]
	v_pk_mul_f32 v[90:91], v[90:91], v[146:147] op_sel_hi:[1,0]
	v_pk_mul_f32 v[172:173], v[84:85], v[252:253] op_sel_hi:[1,0]
	v_pk_mul_f32 v[174:175], v[86:87], v[252:253] op_sel_hi:[1,0]
	v_pk_mul_f32 v[176:177], v[80:81], v[252:253] op_sel_hi:[1,0]
	v_pk_mul_f32 v[178:179], v[82:83], v[252:253] op_sel_hi:[1,0]
	v_exp_f32_e32 v172, v172
	v_exp_f32_e32 v173, v173
	v_exp_f32_e32 v174, v174
	v_exp_f32_e32 v175, v175
	v_exp_f32_e32 v176, v176
	v_exp_f32_e32 v177, v177
	v_exp_f32_e32 v178, v178
	v_exp_f32_e32 v179, v179
	v_pk_add_f32 v[172:173], v[172:173], v[252:253] op_sel:[0,1]
	v_pk_add_f32 v[174:175], v[174:175], v[252:253] op_sel:[0,1]
	v_pk_add_f32 v[176:177], v[176:177], v[252:253] op_sel:[0,1]
	v_pk_add_f32 v[178:179], v[178:179], v[252:253] op_sel:[0,1]
	v_rcp_f32_e32 v172, v172
	v_rcp_f32_e32 v173, v173
	v_rcp_f32_e32 v174, v174
	v_rcp_f32_e32 v175, v175
	v_rcp_f32_e32 v176, v176
	v_rcp_f32_e32 v177, v177
	v_rcp_f32_e32 v178, v178
	v_rcp_f32_e32 v179, v179
	v_pk_mul_f32 v[84:85], v[84:85], v[172:173]
	v_pk_mul_f32 v[86:87], v[86:87], v[174:175]
	v_pk_mul_f32 v[80:81], v[80:81], v[176:177]
	v_pk_mul_f32 v[82:83], v[82:83], v[178:179]
	v_pk_mul_f32 v[84:85], v[92:93], v[84:85]
	v_pk_mul_f32 v[86:87], v[94:95], v[86:87]
	v_pk_mul_f32 v[80:81], v[88:89], v[80:81]
	v_pk_mul_f32 v[82:83], v[90:91], v[82:83]
	v_cvt_pk_bf16_f32 v88, v84, v85
	v_cvt_pk_bf16_f32 v89, v86, v87
	v_cvt_pk_bf16_f32 v90, v80, v81
	v_cvt_pk_bf16_f32 v91, v82, v83
	global_store_dwordx4 v147, v[88:91], s[8:9] sc1
	s_waitcnt vmcnt(11)
	v_add_f32_e32 v180, v180, v181
	v_add_f32_e32 v182, v182, v183
	v_add_f32_e32 v184, v184, v185
	v_add_f32_e32 v186, v186, v187
	v_add_f32_e32 v180, v180, v182
	v_add_f32_e32 v184, v184, v186
	v_add_f32_e32 v180, v180, v184
	v_fmamk_f32 v180, v180, 0x3a000000, v154
	v_rsq_f32_e32 v146, v180
	v_add_u32_e32 v147, 0x84000, v155
	v_pk_mul_f32 v[68:69], v[68:69], v[146:147] op_sel_hi:[1,0]
	v_pk_mul_f32 v[70:71], v[70:71], v[146:147] op_sel_hi:[1,0]
	v_pk_mul_f32 v[64:65], v[64:65], v[146:147] op_sel_hi:[1,0]
	v_pk_mul_f32 v[66:67], v[66:67], v[146:147] op_sel_hi:[1,0]
	v_pk_mul_f32 v[76:77], v[76:77], v[146:147] op_sel_hi:[1,0]
	v_pk_mul_f32 v[78:79], v[78:79], v[146:147] op_sel_hi:[1,0]
	v_pk_mul_f32 v[72:73], v[72:73], v[146:147] op_sel_hi:[1,0]
	v_pk_mul_f32 v[74:75], v[74:75], v[146:147] op_sel_hi:[1,0]
	v_pk_mul_f32 v[180:181], v[68:69], v[252:253] op_sel_hi:[1,0]
	v_pk_mul_f32 v[182:183], v[70:71], v[252:253] op_sel_hi:[1,0]
	v_pk_mul_f32 v[184:185], v[64:65], v[252:253] op_sel_hi:[1,0]
	v_pk_mul_f32 v[186:187], v[66:67], v[252:253] op_sel_hi:[1,0]
	v_exp_f32_e32 v180, v180
	v_exp_f32_e32 v181, v181
	v_exp_f32_e32 v182, v182
	v_exp_f32_e32 v183, v183
	v_exp_f32_e32 v184, v184
	v_exp_f32_e32 v185, v185
	v_exp_f32_e32 v186, v186
	v_exp_f32_e32 v187, v187
	v_pk_add_f32 v[180:181], v[180:181], v[252:253] op_sel:[0,1]
	v_pk_add_f32 v[182:183], v[182:183], v[252:253] op_sel:[0,1]
	v_pk_add_f32 v[184:185], v[184:185], v[252:253] op_sel:[0,1]
	v_pk_add_f32 v[186:187], v[186:187], v[252:253] op_sel:[0,1]
	v_rcp_f32_e32 v180, v180
	v_rcp_f32_e32 v181, v181
	v_rcp_f32_e32 v182, v182
	v_rcp_f32_e32 v183, v183
	v_rcp_f32_e32 v184, v184
	v_rcp_f32_e32 v185, v185
	v_rcp_f32_e32 v186, v186
	v_rcp_f32_e32 v187, v187
	v_pk_mul_f32 v[68:69], v[68:69], v[180:181]
	v_pk_mul_f32 v[70:71], v[70:71], v[182:183]
	v_pk_mul_f32 v[64:65], v[64:65], v[184:185]
	v_pk_mul_f32 v[66:67], v[66:67], v[186:187]
	v_pk_mul_f32 v[68:69], v[76:77], v[68:69]
	v_pk_mul_f32 v[70:71], v[78:79], v[70:71]
	v_pk_mul_f32 v[64:65], v[72:73], v[64:65]
	v_pk_mul_f32 v[66:67], v[74:75], v[66:67]
	v_cvt_pk_bf16_f32 v72, v68, v69
	v_cvt_pk_bf16_f32 v73, v70, v71
	v_cvt_pk_bf16_f32 v74, v64, v65
	v_cvt_pk_bf16_f32 v75, v66, v67
	global_store_dwordx4 v147, v[72:75], s[8:9] sc1
	s_waitcnt vmcnt(10)
	v_add_f32_e32 v188, v188, v189
	v_add_f32_e32 v190, v190, v191
	v_add_f32_e32 v192, v192, v193
	v_add_f32_e32 v194, v194, v195
	v_add_f32_e32 v188, v188, v190
	v_add_f32_e32 v192, v192, v194
	v_add_f32_e32 v188, v188, v192
	v_fmamk_f32 v188, v188, 0x3a000000, v154
	v_rsq_f32_e32 v146, v188
	v_add_u32_e32 v147, 0x160000, v155
	v_pk_mul_f32 v[52:53], v[52:53], v[146:147] op_sel_hi:[1,0]
	v_pk_mul_f32 v[54:55], v[54:55], v[146:147] op_sel_hi:[1,0]
	v_pk_mul_f32 v[48:49], v[48:49], v[146:147] op_sel_hi:[1,0]
	v_pk_mul_f32 v[50:51], v[50:51], v[146:147] op_sel_hi:[1,0]
	v_pk_mul_f32 v[60:61], v[60:61], v[146:147] op_sel_hi:[1,0]
	v_pk_mul_f32 v[62:63], v[62:63], v[146:147] op_sel_hi:[1,0]
	v_pk_mul_f32 v[56:57], v[56:57], v[146:147] op_sel_hi:[1,0]
	v_pk_mul_f32 v[58:59], v[58:59], v[146:147] op_sel_hi:[1,0]
	v_pk_mul_f32 v[188:189], v[52:53], v[252:253] op_sel_hi:[1,0]
	v_pk_mul_f32 v[190:191], v[54:55], v[252:253] op_sel_hi:[1,0]
	v_pk_mul_f32 v[192:193], v[48:49], v[252:253] op_sel_hi:[1,0]
	v_pk_mul_f32 v[194:195], v[50:51], v[252:253] op_sel_hi:[1,0]
	v_exp_f32_e32 v188, v188
	v_exp_f32_e32 v189, v189
	v_exp_f32_e32 v190, v190
	v_exp_f32_e32 v191, v191
	v_exp_f32_e32 v192, v192
	v_exp_f32_e32 v193, v193
	v_exp_f32_e32 v194, v194
	v_exp_f32_e32 v195, v195
	v_pk_add_f32 v[188:189], v[188:189], v[252:253] op_sel:[0,1]
	v_pk_add_f32 v[190:191], v[190:191], v[252:253] op_sel:[0,1]
	v_pk_add_f32 v[192:193], v[192:193], v[252:253] op_sel:[0,1]
	v_pk_add_f32 v[194:195], v[194:195], v[252:253] op_sel:[0,1]
	v_rcp_f32_e32 v188, v188
	v_rcp_f32_e32 v189, v189
	v_rcp_f32_e32 v190, v190
	v_rcp_f32_e32 v191, v191
	v_rcp_f32_e32 v192, v192
	v_rcp_f32_e32 v193, v193
	v_rcp_f32_e32 v194, v194
	v_rcp_f32_e32 v195, v195
	v_pk_mul_f32 v[52:53], v[52:53], v[188:189]
	v_pk_mul_f32 v[54:55], v[54:55], v[190:191]
	v_pk_mul_f32 v[48:49], v[48:49], v[192:193]
	v_pk_mul_f32 v[50:51], v[50:51], v[194:195]
	v_pk_mul_f32 v[52:53], v[60:61], v[52:53]
	v_pk_mul_f32 v[54:55], v[62:63], v[54:55]
	v_pk_mul_f32 v[48:49], v[56:57], v[48:49]
	v_pk_mul_f32 v[50:51], v[58:59], v[50:51]
	v_cvt_pk_bf16_f32 v56, v52, v53
	v_cvt_pk_bf16_f32 v57, v54, v55
	v_cvt_pk_bf16_f32 v58, v48, v49
	v_cvt_pk_bf16_f32 v59, v50, v51
	global_store_dwordx4 v147, v[56:59], s[8:9] sc1
	s_waitcnt vmcnt(9)
	v_add_f32_e32 v196, v196, v197
	v_add_f32_e32 v198, v198, v199
	v_add_f32_e32 v200, v200, v201
	v_add_f32_e32 v202, v202, v203
	v_add_f32_e32 v196, v196, v198
	v_add_f32_e32 v200, v200, v202
	v_add_f32_e32 v196, v196, v200
	v_fmamk_f32 v196, v196, 0x3a000000, v154
	v_rsq_f32_e32 v146, v196
	v_add_u32_e32 v147, 0x18c000, v155
	v_pk_mul_f32 v[36:37], v[36:37], v[146:147] op_sel_hi:[1,0]
	v_pk_mul_f32 v[38:39], v[38:39], v[146:147] op_sel_hi:[1,0]
	v_pk_mul_f32 v[32:33], v[32:33], v[146:147] op_sel_hi:[1,0]
	v_pk_mul_f32 v[34:35], v[34:35], v[146:147] op_sel_hi:[1,0]
	v_pk_mul_f32 v[44:45], v[44:45], v[146:147] op_sel_hi:[1,0]
	v_pk_mul_f32 v[46:47], v[46:47], v[146:147] op_sel_hi:[1,0]
	v_pk_mul_f32 v[40:41], v[40:41], v[146:147] op_sel_hi:[1,0]
	v_pk_mul_f32 v[42:43], v[42:43], v[146:147] op_sel_hi:[1,0]
	v_pk_mul_f32 v[196:197], v[36:37], v[252:253] op_sel_hi:[1,0]
	v_pk_mul_f32 v[198:199], v[38:39], v[252:253] op_sel_hi:[1,0]
	v_pk_mul_f32 v[200:201], v[32:33], v[252:253] op_sel_hi:[1,0]
	v_pk_mul_f32 v[202:203], v[34:35], v[252:253] op_sel_hi:[1,0]
	v_exp_f32_e32 v196, v196
	v_exp_f32_e32 v197, v197
	v_exp_f32_e32 v198, v198
	v_exp_f32_e32 v199, v199
	v_exp_f32_e32 v200, v200
	v_exp_f32_e32 v201, v201
	v_exp_f32_e32 v202, v202
	v_exp_f32_e32 v203, v203
	v_pk_add_f32 v[196:197], v[196:197], v[252:253] op_sel:[0,1]
	v_pk_add_f32 v[198:199], v[198:199], v[252:253] op_sel:[0,1]
	v_pk_add_f32 v[200:201], v[200:201], v[252:253] op_sel:[0,1]
	v_pk_add_f32 v[202:203], v[202:203], v[252:253] op_sel:[0,1]
	v_rcp_f32_e32 v196, v196
	v_rcp_f32_e32 v197, v197
	v_rcp_f32_e32 v198, v198
	v_rcp_f32_e32 v199, v199
	v_rcp_f32_e32 v200, v200
	v_rcp_f32_e32 v201, v201
	v_rcp_f32_e32 v202, v202
	v_rcp_f32_e32 v203, v203
	v_pk_mul_f32 v[36:37], v[36:37], v[196:197]
	v_pk_mul_f32 v[38:39], v[38:39], v[198:199]
	v_pk_mul_f32 v[32:33], v[32:33], v[200:201]
	v_pk_mul_f32 v[34:35], v[34:35], v[202:203]
	v_pk_mul_f32 v[36:37], v[44:45], v[36:37]
	v_pk_mul_f32 v[38:39], v[46:47], v[38:39]
	v_pk_mul_f32 v[32:33], v[40:41], v[32:33]
	v_pk_mul_f32 v[34:35], v[42:43], v[34:35]
	v_cvt_pk_bf16_f32 v40, v36, v37
	v_cvt_pk_bf16_f32 v41, v38, v39
	v_cvt_pk_bf16_f32 v42, v32, v33
	v_cvt_pk_bf16_f32 v43, v34, v35
	global_store_dwordx4 v147, v[40:43], s[8:9] sc1
	s_waitcnt vmcnt(8)
	v_add_f32_e32 v204, v204, v205
	v_add_f32_e32 v206, v206, v207
	v_add_f32_e32 v208, v208, v209
	v_add_f32_e32 v210, v210, v211
	v_add_f32_e32 v204, v204, v206
	v_add_f32_e32 v208, v208, v210
	v_add_f32_e32 v204, v204, v208
	v_fmamk_f32 v204, v204, 0x3a000000, v154
	v_rsq_f32_e32 v146, v204
	v_add_u32_e32 v147, 0x1b8000, v155
	v_pk_mul_f32 v[20:21], v[20:21], v[146:147] op_sel_hi:[1,0]
	v_pk_mul_f32 v[22:23], v[22:23], v[146:147] op_sel_hi:[1,0]
	v_pk_mul_f32 v[16:17], v[16:17], v[146:147] op_sel_hi:[1,0]
	v_pk_mul_f32 v[18:19], v[18:19], v[146:147] op_sel_hi:[1,0]
	v_pk_mul_f32 v[28:29], v[28:29], v[146:147] op_sel_hi:[1,0]
	v_pk_mul_f32 v[30:31], v[30:31], v[146:147] op_sel_hi:[1,0]
	v_pk_mul_f32 v[24:25], v[24:25], v[146:147] op_sel_hi:[1,0]
	v_pk_mul_f32 v[26:27], v[26:27], v[146:147] op_sel_hi:[1,0]
	v_pk_mul_f32 v[204:205], v[20:21], v[252:253] op_sel_hi:[1,0]
	v_pk_mul_f32 v[206:207], v[22:23], v[252:253] op_sel_hi:[1,0]
	v_pk_mul_f32 v[208:209], v[16:17], v[252:253] op_sel_hi:[1,0]
	v_pk_mul_f32 v[210:211], v[18:19], v[252:253] op_sel_hi:[1,0]
	v_exp_f32_e32 v204, v204
	v_exp_f32_e32 v205, v205
	v_exp_f32_e32 v206, v206
	v_exp_f32_e32 v207, v207
	v_exp_f32_e32 v208, v208
	v_exp_f32_e32 v209, v209
	v_exp_f32_e32 v210, v210
	v_exp_f32_e32 v211, v211
	v_pk_add_f32 v[204:205], v[204:205], v[252:253] op_sel:[0,1]
	v_pk_add_f32 v[206:207], v[206:207], v[252:253] op_sel:[0,1]
	v_pk_add_f32 v[208:209], v[208:209], v[252:253] op_sel:[0,1]
	v_pk_add_f32 v[210:211], v[210:211], v[252:253] op_sel:[0,1]
	v_rcp_f32_e32 v204, v204
	v_rcp_f32_e32 v205, v205
	v_rcp_f32_e32 v206, v206
	v_rcp_f32_e32 v207, v207
	v_rcp_f32_e32 v208, v208
	v_rcp_f32_e32 v209, v209
	v_rcp_f32_e32 v210, v210
	v_rcp_f32_e32 v211, v211
	v_pk_mul_f32 v[20:21], v[20:21], v[204:205]
	v_pk_mul_f32 v[22:23], v[22:23], v[206:207]
	v_pk_mul_f32 v[16:17], v[16:17], v[208:209]
	v_pk_mul_f32 v[18:19], v[18:19], v[210:211]
	v_pk_mul_f32 v[20:21], v[28:29], v[20:21]
	v_pk_mul_f32 v[22:23], v[30:31], v[22:23]
	v_pk_mul_f32 v[16:17], v[24:25], v[16:17]
	v_pk_mul_f32 v[18:19], v[26:27], v[18:19]
	v_cvt_pk_bf16_f32 v24, v20, v21
	v_cvt_pk_bf16_f32 v25, v22, v23
	v_cvt_pk_bf16_f32 v26, v16, v17
	v_cvt_pk_bf16_f32 v27, v18, v19
	global_store_dwordx4 v147, v[24:27], s[8:9] sc1
	s_waitcnt vmcnt(7)
	v_add_f32_e32 v212, v212, v213
	v_add_f32_e32 v214, v214, v215
	v_add_f32_e32 v216, v216, v217
	v_add_f32_e32 v218, v218, v219
	v_add_f32_e32 v212, v212, v214
	v_add_f32_e32 v216, v216, v218
	v_add_f32_e32 v212, v212, v216
	v_fmamk_f32 v212, v212, 0x3a000000, v154
	v_rsq_f32_e32 v146, v212
	v_add_u32_e32 v147, 0x1e4000, v155
	v_pk_mul_f32 v[8:9], v[8:9], v[146:147] op_sel_hi:[1,0]
	v_pk_mul_f32 v[10:11], v[10:11], v[146:147] op_sel_hi:[1,0]
	v_pk_mul_f32 v[0:1], v[0:1], v[146:147] op_sel_hi:[1,0]
	v_pk_mul_f32 v[2:3], v[2:3], v[146:147] op_sel_hi:[1,0]
	v_pk_mul_f32 v[12:13], v[12:13], v[146:147] op_sel_hi:[1,0]
	v_pk_mul_f32 v[14:15], v[14:15], v[146:147] op_sel_hi:[1,0]
	v_pk_mul_f32 v[4:5], v[4:5], v[146:147] op_sel_hi:[1,0]
	v_pk_mul_f32 v[6:7], v[6:7], v[146:147] op_sel_hi:[1,0]
	v_pk_mul_f32 v[212:213], v[8:9], v[252:253] op_sel_hi:[1,0]
	v_pk_mul_f32 v[214:215], v[10:11], v[252:253] op_sel_hi:[1,0]
	v_pk_mul_f32 v[216:217], v[0:1], v[252:253] op_sel_hi:[1,0]
	v_pk_mul_f32 v[218:219], v[2:3], v[252:253] op_sel_hi:[1,0]
	v_exp_f32_e32 v212, v212
	v_exp_f32_e32 v213, v213
	v_exp_f32_e32 v214, v214
	v_exp_f32_e32 v215, v215
	v_exp_f32_e32 v216, v216
	v_exp_f32_e32 v217, v217
	v_exp_f32_e32 v218, v218
	v_exp_f32_e32 v219, v219
	v_pk_add_f32 v[212:213], v[212:213], v[252:253] op_sel:[0,1]
	v_pk_add_f32 v[214:215], v[214:215], v[252:253] op_sel:[0,1]
	v_pk_add_f32 v[216:217], v[216:217], v[252:253] op_sel:[0,1]
	v_pk_add_f32 v[218:219], v[218:219], v[252:253] op_sel:[0,1]
	v_rcp_f32_e32 v212, v212
	v_rcp_f32_e32 v213, v213
	v_rcp_f32_e32 v214, v214
	v_rcp_f32_e32 v215, v215
	v_rcp_f32_e32 v216, v216
	v_rcp_f32_e32 v217, v217
	v_rcp_f32_e32 v218, v218
	v_rcp_f32_e32 v219, v219
	v_pk_mul_f32 v[8:9], v[8:9], v[212:213]
	v_pk_mul_f32 v[10:11], v[10:11], v[214:215]
	v_pk_mul_f32 v[0:1], v[0:1], v[216:217]
	v_pk_mul_f32 v[2:3], v[2:3], v[218:219]
	v_pk_mul_f32 v[8:9], v[12:13], v[8:9]
	v_pk_mul_f32 v[10:11], v[14:15], v[10:11]
	v_pk_mul_f32 v[0:1], v[4:5], v[0:1]
	v_pk_mul_f32 v[2:3], v[6:7], v[2:3]
	v_cvt_pk_bf16_f32 v4, v8, v9
	v_cvt_pk_bf16_f32 v5, v10, v11
	v_cvt_pk_bf16_f32 v6, v0, v1
	v_cvt_pk_bf16_f32 v7, v2, v3
	global_store_dwordx4 v147, v[4:7], s[8:9] sc1
	s_cbranch_vccnz .LBB0_667
	s_andn2_b64 vcc, exec, s[6:7]
	s_cbranch_vccnz .LBB0_666
	s_barrier
	s_branch .LBB0_666
